# accumulator zeroing hoisted above the first prologue DMA wait in 7 single-loop GEMM phases (copy on unit-loop latch), K-loop placement kept
# speedup vs baseline: 1.0071x; 1.0071x over previous
.LBB0_140:
	s_add_u32 s14, s28, 0x4300000
	s_addc_u32 s15, s29, 0
	s_add_u32 s18, s28, 0x6300000
	s_addc_u32 s19, s29, 0
	s_add_u32 s52, s28, 0x8400000
	s_addc_u32 s53, s29, 0
	s_add_u32 s54, s28, 0xa500000
	s_mov_b64 s[56:57], 0x80
	s_addc_u32 s55, s29, 0
	s_and_b32 s94, s11, 3
	s_add_i32 m0, s68, 0x18000
	v_lshl_add_u64 v[8:9], v[8:9], 0, s[56:57]
	s_lshl_b32 s95, s0, 6
	s_lshl_b32 s6, s0, 13
	s_lshl_b32 s7, s94, 12
	v_mov_b64_e32 v[10:11], 0
	v_mov_b64_e32 v[12:13], 0
	v_mov_b64_e32 v[14:15], 0
	v_mov_b64_e32 v[24:25], 0
	v_mov_b64_e32 v[36:37], 0
	v_mov_b64_e32 v[38:39], 0
	v_mov_b64_e32 v[40:41], 0
	v_mov_b64_e32 v[42:43], 0
	v_mov_b64_e32 v[44:45], 0
	v_mov_b64_e32 v[46:47], 0
	v_mov_b64_e32 v[64:65], 0
	v_mov_b64_e32 v[66:67], 0
	v_mov_b64_e32 v[68:69], 0
	v_mov_b64_e32 v[70:71], 0
	v_mov_b64_e32 v[72:73], 0
	v_mov_b64_e32 v[74:75], 0
	v_mov_b64_e32 v[76:77], 0
	v_mov_b64_e32 v[78:79], 0
	v_mov_b64_e32 v[80:81], 0
	v_mov_b64_e32 v[82:83], 0
	v_mov_b64_e32 v[84:85], 0
	v_mov_b64_e32 v[86:87], 0
	v_mov_b64_e32 v[88:89], 0
	v_mov_b64_e32 v[90:91], 0
	v_mov_b64_e32 v[92:93], 0
	v_mov_b64_e32 v[94:95], 0
	v_mov_b64_e32 v[96:97], 0
	v_mov_b64_e32 v[98:99], 0
	v_mov_b64_e32 v[100:101], 0
	v_mov_b64_e32 v[102:103], 0
	v_mov_b64_e32 v[104:105], 0
	v_mov_b64_e32 v[106:107], 0
	v_mov_b64_e32 v[108:109], 0
	v_mov_b64_e32 v[110:111], 0
	v_mov_b64_e32 v[112:113], 0
	v_mov_b64_e32 v[114:115], 0
	v_mov_b64_e32 v[116:117], 0
	v_mov_b64_e32 v[118:119], 0
	v_mov_b64_e32 v[120:121], 0
	v_mov_b64_e32 v[122:123], 0
	v_mov_b64_e32 v[124:125], 0
	v_mov_b64_e32 v[126:127], 0
	v_mov_b64_e32 v[128:129], 0
	v_mov_b64_e32 v[130:131], 0
	v_mov_b64_e32 v[132:133], 0
	v_mov_b64_e32 v[134:135], 0
	v_mov_b64_e32 v[136:137], 0
	v_mov_b64_e32 v[138:139], 0
	v_mov_b64_e32 v[140:141], 0
	v_mov_b64_e32 v[142:143], 0
	s_waitcnt vmcnt(2)
	s_barrier
	global_load_lds_dwordx4 v[8:9], off
	v_lshl_add_u64 v[2:3], v[2:3], 0, s[56:57]
	s_add_i32 m0, s68, 0x1a000
	s_add_i32 s96, s68, 0x8000
	s_add_i32 s71, s68, 0xa000
	global_load_lds_dwordx4 v[2:3], off
	v_lshl_add_u64 v[0:1], v[0:1], 0, s[56:57]
	s_mov_b32 m0, s96
	s_add_u32 s0, s4, 0x40080
	global_load_lds_dwordx4 v[0:1], off
	v_lshl_add_u64 v[0:1], v[6:7], 0, s[56:57]
	s_mov_b32 m0, s71
	s_addc_u32 s1, s5, 0
	global_load_lds_dwordx4 v[0:1], off
	s_add_i32 m0, s68, 0x1c000
	v_lshl_add_u64 v[0:1], s[0:1], 0, v[146:147]
	global_load_lds_dwordx4 v[0:1], off
	v_lshl_add_u64 v[0:1], s[0:1], 0, v[150:151]
	s_add_i32 m0, s68, 0x1e000
	s_cmpk_lt_u32 s10, 0x100
	global_load_lds_dwordx4 v[0:1], off
	v_bfe_u32 v0, v26, 4, 2
	v_lshlrev_b32_e32 v154, 4, v0
	v_lshlrev_b32_e32 v152, 3, v0
	v_lshl_or_b32 v0, v153, 6, v154
	v_and_b32_e32 v1, 32, v4
	v_bitop3_b32 v2, v0, s6, v1 bitop3:0xde
	v_bitop3_b32 v167, v0, s7, v1 bitop3:0xde
	v_lshlrev_b32_e32 v0, 14, v27
	v_and_b32_e32 v0, 0xffff8000, v0
	v_lshl_add_u32 v0, v28, 11, v0
	v_and_b32_e32 v1, 1, v27
	v_lshl_or_b32 v0, v1, 6, v0
	v_lshl_add_u32 v158, v29, 1, v0
	v_lshlrev_b32_e32 v0, 14, v30
	v_and_b32_e32 v0, 0xffff8000, v0
	v_lshl_add_u32 v0, v31, 11, v0
	v_and_b32_e32 v1, 1, v30
	s_waitcnt vmcnt(6)
	v_lshl_or_b32 v0, v1, 6, v0
	s_cselect_b64 s[58:59], -1, 0
	v_mov_b32_e32 v155, 0
	v_lshl_add_u32 v160, v32, 1, v0
	s_add_i32 s72, 0, 0x10000
	s_add_i32 s73, 0, 0x14000
	v_mbcnt_lo_u32_b32 v0, -1, 0
	s_mov_b32 s76, 0
	s_ashr_i32 s10, s17, 31
	s_ashr_i32 s11, s16, 31
	v_lshl_add_u64 v[156:157], s[74:75], 0, v[154:155]
	v_mov_b32_e32 v159, v155
	v_mov_b32_e32 v161, v155
	v_mov_b64_e32 v[162:163], 0x400
	v_mov_b64_e32 v[164:165], 0x3ff
	v_add_u32_e32 v214, s72, v167
	v_add_u32_e32 v215, s73, v167
	v_add_u32_e32 v216, 0, v2
	v_mbcnt_hi_u32_b32 v217, -1, v0
	v_lshlrev_b32_e32 v218, 2, v152
	s_mov_b32 s60, 0x3a800000
	s_mov_b32 s12, 0x800000
	v_mov_b32_e32 v166, 0x358637bd
	v_mov_b32_e32 v219, 0x3e38aa3b
	s_waitcnt vmcnt(6)
	v_add_f32_e32 v240, v241, v240
	v_add_f32_e32 v241, v242, v243
	v_add_f32_e32 v244, v245, v244
	v_add_f32_e32 v245, v246, v247
	v_add_f32_e32 v242, v244, v245
	v_add_f32_e32 v243, v240, v241
	ds_bpermute_b32 v247, v238, v243
	ds_bpermute_b32 v246, v238, v242
	s_waitcnt lgkmcnt(0)
	v_pk_add_f32 v[250:251], v[242:243], v[246:247]
	ds_bpermute_b32 v253, v239, v251
	ds_bpermute_b32 v252, v239, v250
	s_waitcnt lgkmcnt(0)
	v_pk_add_f32 v[250:251], v[250:251], v[252:253]
	s_lshl_b32 s99, s98, 7
	v_lshl_add_u32 v236, v233, 2, s99
	v_add_u32_e32 v236, 0x22800, v236
	ds_write_b32 v236, v251
	ds_write_b32 v236, v250 offset:64
	v_add_u32_e32 v237, 0x22c00, v237
	ds_write_b32 v237, v248
	ds_write_b32 v237, v249 offset:256
	s_waitcnt lgkmcnt(0)
	s_barrier
	s_branch .LBB0_143

.LBB0_142:
	s_andn2_b64 vcc, exec, s[0:1]
	s_mov_b32 s92, s13
	s_mov_b32 s86, s97
	s_mov_b64 s[4:5], s[84:85]
	s_mov_b64 s[2:3], s[82:83]
	s_cbranch_vccz .LBB0_294
	v_mov_b64_e32 v[10:11], 0
	v_mov_b64_e32 v[12:13], 0
	v_mov_b64_e32 v[14:15], 0
	v_mov_b64_e32 v[24:25], 0
	v_mov_b64_e32 v[36:37], 0
	v_mov_b64_e32 v[38:39], 0
	v_mov_b64_e32 v[40:41], 0
	v_mov_b64_e32 v[42:43], 0
	v_mov_b64_e32 v[44:45], 0
	v_mov_b64_e32 v[46:47], 0
	v_mov_b64_e32 v[64:65], 0
	v_mov_b64_e32 v[66:67], 0
	v_mov_b64_e32 v[68:69], 0
	v_mov_b64_e32 v[70:71], 0
	v_mov_b64_e32 v[72:73], 0
	v_mov_b64_e32 v[74:75], 0
	v_mov_b64_e32 v[76:77], 0
	v_mov_b64_e32 v[78:79], 0
	v_mov_b64_e32 v[80:81], 0
	v_mov_b64_e32 v[82:83], 0
	v_mov_b64_e32 v[84:85], 0
	v_mov_b64_e32 v[86:87], 0
	v_mov_b64_e32 v[88:89], 0
	v_mov_b64_e32 v[90:91], 0
	v_mov_b64_e32 v[92:93], 0
	v_mov_b64_e32 v[94:95], 0
	v_mov_b64_e32 v[96:97], 0
	v_mov_b64_e32 v[98:99], 0
	v_mov_b64_e32 v[100:101], 0
	v_mov_b64_e32 v[102:103], 0
	v_mov_b64_e32 v[104:105], 0
	v_mov_b64_e32 v[106:107], 0
	v_mov_b64_e32 v[108:109], 0
	v_mov_b64_e32 v[110:111], 0
	v_mov_b64_e32 v[112:113], 0
	v_mov_b64_e32 v[114:115], 0
	v_mov_b64_e32 v[116:117], 0
	v_mov_b64_e32 v[118:119], 0
	v_mov_b64_e32 v[120:121], 0
	v_mov_b64_e32 v[122:123], 0
	v_mov_b64_e32 v[124:125], 0
	v_mov_b64_e32 v[126:127], 0
	v_mov_b64_e32 v[128:129], 0
	v_mov_b64_e32 v[130:131], 0
	v_mov_b64_e32 v[132:133], 0
	v_mov_b64_e32 v[134:135], 0
	v_mov_b64_e32 v[136:137], 0
	v_mov_b64_e32 v[138:139], 0
	v_mov_b64_e32 v[140:141], 0
	v_mov_b64_e32 v[142:143], 0

.LBB0_149:
	s_ashr_i32 s79, s78, 31
	s_lshl_b64 s[6:7], s[78:79], 11
	s_add_u32 s82, s34, s6
	s_addc_u32 s83, s35, s7
	s_and_b64 s[6:7], s[0:1], exec
	s_cselect_b32 s8, s83, s3
	s_cselect_b32 s9, s82, s2
	s_ashr_i32 s81, s80, 31
	s_lshl_b64 s[6:7], s[80:81], 11
	s_add_u32 s84, s40, s6
	s_addc_u32 s85, s41, s7
	s_and_b64 s[6:7], s[0:1], exec
	s_cselect_b32 s79, s85, s5
	s_cselect_b32 s81, s84, s4
	s_add_u32 s2, s2, 0x40080
	s_addc_u32 s3, s3, 0
	s_add_u32 s87, s4, 0x100
	v_mov_b32_e32 v0, 0
	s_addc_u32 s88, s5, 0
	s_mov_b32 s89, -2
	v_mov_b32_e32 v1, v0
	v_mov_b32_e32 v2, v0
	v_mov_b32_e32 v3, v0
	v_mov_b32_e32 v4, v0
	v_mov_b32_e32 v5, v0
	v_mov_b32_e32 v6, v0
	v_mov_b32_e32 v7, v0
	v_mov_b32_e32 v16, v0
	v_mov_b32_e32 v17, v0
	v_mov_b32_e32 v18, v0
	v_mov_b32_e32 v19, v0
	v_mov_b32_e32 v20, v0
	v_mov_b32_e32 v21, v0
	v_mov_b32_e32 v22, v0
	v_mov_b32_e32 v23, v0
	v_mov_b32_e32 v32, v0
	v_mov_b32_e32 v33, v0
	v_mov_b32_e32 v34, v0
	v_mov_b32_e32 v35, v0
	s_waitcnt vmcnt(0)
	v_mov_b64_e32 v[8:9], 0
	v_mov_b64_e32 v[26:27], 0
	v_mov_b64_e32 v[28:29], 0
	v_mov_b64_e32 v[30:31], 0
	s_nop 0
	s_nop 0
	s_nop 0
	s_nop 0
	s_nop 0
	s_nop 0
	s_nop 0
	s_nop 0
	s_nop 0
	s_nop 0
	s_nop 0
	s_nop 0
	s_nop 0
	s_nop 0

.LBB0_732:
	s_mov_b64 s[8:9], 0x80
	s_and_b32 s66, s6, 3
	s_add_i32 m0, s62, 0x18000
	v_lshl_add_u64 v[6:7], v[6:7], 0, s[8:9]
	s_lshl_b32 s2, s10, 13
	s_lshl_b32 s3, s66, 12
	v_mov_b32_e32 v15, 0
	v_mov_b64_e32 v[24:25], 0
	v_mov_b64_e32 v[26:27], 0
	v_mov_b64_e32 v[28:29], 0
	v_mov_b64_e32 v[30:31], 0
	v_mov_b64_e32 v[36:37], 0
	v_mov_b64_e32 v[38:39], 0
	v_mov_b64_e32 v[40:41], 0
	v_mov_b64_e32 v[42:43], 0
	v_mov_b64_e32 v[44:45], 0
	v_mov_b64_e32 v[46:47], 0
	v_mov_b64_e32 v[48:49], 0
	v_mov_b64_e32 v[50:51], 0
	v_mov_b64_e32 v[52:53], 0
	v_mov_b64_e32 v[54:55], 0
	v_mov_b64_e32 v[56:57], 0
	v_mov_b64_e32 v[58:59], 0
	v_mov_b64_e32 v[60:61], 0
	v_mov_b64_e32 v[62:63], 0
	v_mov_b64_e32 v[64:65], 0
	v_mov_b64_e32 v[66:67], 0
	v_mov_b64_e32 v[68:69], 0
	v_mov_b64_e32 v[70:71], 0
	v_mov_b64_e32 v[72:73], 0
	v_mov_b64_e32 v[74:75], 0
	v_mov_b64_e32 v[76:77], 0
	v_mov_b64_e32 v[78:79], 0
	v_mov_b64_e32 v[80:81], 0
	v_mov_b64_e32 v[82:83], 0
	v_mov_b64_e32 v[84:85], 0
	v_mov_b64_e32 v[86:87], 0
	v_mov_b64_e32 v[88:89], 0
	v_mov_b64_e32 v[90:91], 0
	v_mov_b64_e32 v[92:93], 0
	v_mov_b64_e32 v[94:95], 0
	v_mov_b64_e32 v[96:97], 0
	v_mov_b64_e32 v[98:99], 0
	v_mov_b64_e32 v[100:101], 0
	v_mov_b64_e32 v[102:103], 0
	v_mov_b64_e32 v[104:105], 0
	v_mov_b64_e32 v[106:107], 0
	v_mov_b64_e32 v[108:109], 0
	v_mov_b64_e32 v[110:111], 0
	v_mov_b64_e32 v[112:113], 0
	v_mov_b64_e32 v[114:115], 0
	v_mov_b64_e32 v[116:117], 0
	v_mov_b64_e32 v[118:119], 0
	v_mov_b64_e32 v[120:121], 0
	v_mov_b64_e32 v[122:123], 0
	v_mov_b64_e32 v[124:125], 0
	v_mov_b64_e32 v[126:127], 0
	s_waitcnt vmcnt(2)
	s_barrier
	global_load_lds_dwordx4 v[6:7], off
	v_lshl_add_u64 v[4:5], v[4:5], 0, s[8:9]
	s_add_i32 m0, s62, 0x1a000
	s_add_i32 s67, s62, 0x8000
	s_add_i32 s68, s62, 0xa000
	global_load_lds_dwordx4 v[4:5], off
	v_lshl_add_u64 v[2:3], v[2:3], 0, s[8:9]
	s_mov_b32 m0, s67
	s_add_u32 s0, s58, 0x40080
	global_load_lds_dwordx4 v[2:3], off
	v_lshl_add_u64 v[0:1], v[0:1], 0, s[8:9]
	s_mov_b32 m0, s68
	s_addc_u32 s1, s59, 0
	global_load_lds_dwordx4 v[0:1], off
	s_add_i32 m0, s62, 0x1c000
	v_lshl_add_u64 v[0:1], s[0:1], 0, v[154:155]
	global_load_lds_dwordx4 v[0:1], off
	v_lshl_add_u64 v[0:1], s[0:1], 0, v[158:159]
	s_add_i32 m0, s62, 0x1e000
	s_add_i32 s71, 0, 0x10000
	global_load_lds_dwordx4 v[0:1], off
	v_bfe_u32 v1, v8, 4, 2
	v_and_b32_e32 v0, 15, v8
	v_lshlrev_b32_e32 v3, 4, v1
	v_lshl_or_b32 v184, s10, 6, v0
	v_lshl_or_b32 v0, v0, 6, v3
	v_lshlrev_b32_e32 v3, 2, v8
	v_and_b32_e32 v3, 32, v3
	v_bitop3_b32 v4, v0, s2, v3 bitop3:0xde
	v_bitop3_b32 v185, v0, s3, v3 bitop3:0xde
	v_lshlrev_b32_e32 v0, 14, v9
	v_and_b32_e32 v0, 0xffff8000, v0
	v_lshlrev_b32_e32 v2, 3, v1
	v_cmp_eq_u32_e64 s[0:1], 0, v1
	v_lshl_add_u32 v0, v10, 11, v0
	v_and_b32_e32 v1, 1, v9
	v_lshl_or_b32 v0, v1, 6, v0
	v_lshl_add_u32 v160, v11, 1, v0
	v_lshlrev_b32_e32 v0, 14, v12
	v_and_b32_e32 v0, 0xffff8000, v0
	v_lshl_add_u32 v0, v13, 11, v0
	v_and_b32_e32 v1, 1, v12
	s_waitcnt vmcnt(6)
	v_lshl_or_b32 v0, v1, 6, v0
	v_lshl_add_u32 v162, v14, 1, v0
	s_add_i32 s72, 0, 0x14000
	v_mbcnt_lo_u32_b32 v0, -1, 0
	v_lshl_or_b32 v186, s66, 5, v2
	s_ashr_i32 s69, s17, 31
	s_ashr_i32 s70, s16, 31
	v_mov_b32_e32 v161, v155
	v_mov_b32_e32 v163, v155
	v_mov_b64_e32 v[164:165], 0x100
	v_mov_b64_e32 v[166:167], 0xff
	v_add_u32_e32 v187, s71, v185
	v_add_u32_e32 v188, s72, v185
	v_add_u32_e32 v189, 0, v4
	v_mbcnt_hi_u32_b32 v190, -1, v0
	s_mov_b32 s73, 0
	s_barrier
	s_branch .LBB0_734
.LBB0_733:
	s_or_b64 exec, exec, s[58:59]
	s_and_b64 vcc, exec, s[2:3]
	s_mov_b32 s78, s76
	s_mov_b32 s79, s77
	s_mov_b64 s[58:59], s[18:19]
	s_mov_b64 s[52:53], s[14:15]
	s_cbranch_vccnz .LBB0_758
	v_mov_b32_e32 v15, 0
	v_mov_b64_e32 v[24:25], 0
	v_mov_b64_e32 v[26:27], 0
	v_mov_b64_e32 v[28:29], 0
	v_mov_b64_e32 v[30:31], 0
	v_mov_b64_e32 v[36:37], 0
	v_mov_b64_e32 v[38:39], 0
	v_mov_b64_e32 v[40:41], 0
	v_mov_b64_e32 v[42:43], 0
	v_mov_b64_e32 v[44:45], 0
	v_mov_b64_e32 v[46:47], 0
	v_mov_b64_e32 v[48:49], 0
	v_mov_b64_e32 v[50:51], 0
	v_mov_b64_e32 v[52:53], 0
	v_mov_b64_e32 v[54:55], 0
	v_mov_b64_e32 v[56:57], 0
	v_mov_b64_e32 v[58:59], 0
	v_mov_b64_e32 v[60:61], 0
	v_mov_b64_e32 v[62:63], 0
	v_mov_b64_e32 v[64:65], 0
	v_mov_b64_e32 v[66:67], 0
	v_mov_b64_e32 v[68:69], 0
	v_mov_b64_e32 v[70:71], 0
	v_mov_b64_e32 v[72:73], 0
	v_mov_b64_e32 v[74:75], 0
	v_mov_b64_e32 v[76:77], 0
	v_mov_b64_e32 v[78:79], 0
	v_mov_b64_e32 v[80:81], 0
	v_mov_b64_e32 v[82:83], 0
	v_mov_b64_e32 v[84:85], 0
	v_mov_b64_e32 v[86:87], 0
	v_mov_b64_e32 v[88:89], 0
	v_mov_b64_e32 v[90:91], 0
	v_mov_b64_e32 v[92:93], 0
	v_mov_b64_e32 v[94:95], 0
	v_mov_b64_e32 v[96:97], 0
	v_mov_b64_e32 v[98:99], 0
	v_mov_b64_e32 v[100:101], 0
	v_mov_b64_e32 v[102:103], 0
	v_mov_b64_e32 v[104:105], 0
	v_mov_b64_e32 v[106:107], 0
	v_mov_b64_e32 v[108:109], 0
	v_mov_b64_e32 v[110:111], 0
	v_mov_b64_e32 v[112:113], 0
	v_mov_b64_e32 v[114:115], 0
	v_mov_b64_e32 v[116:117], 0
	v_mov_b64_e32 v[118:119], 0
	v_mov_b64_e32 v[120:121], 0
	v_mov_b64_e32 v[122:123], 0
	v_mov_b64_e32 v[124:125], 0
	v_mov_b64_e32 v[126:127], 0

.LBB0_740:
	s_ashr_i32 s11, s10, 31
	v_cmp_lt_i64_e32 vcc, s[14:15], v[164:165]
	s_lshl_b64 s[14:15], s[10:11], 11
	s_add_u32 s14, s41, s14
	s_addc_u32 s15, s54, s15
	s_and_b64 s[18:19], vcc, exec
	s_cselect_b32 s6, s15, s53
	s_cselect_b32 s11, s14, s52
	s_ashr_i32 s13, s12, 31
	s_lshl_b64 s[18:19], s[12:13], 11
	s_add_u32 s18, s55, s18
	s_addc_u32 s19, s56, s19
	s_and_b64 s[60:61], vcc, exec
	s_cselect_b32 s13, s19, s59
	s_cselect_b32 s80, s18, s58
	s_add_u32 s52, s52, 0x40080
	s_addc_u32 s53, s53, 0
	s_add_u32 s81, s58, 0x100
	v_mov_b32_e32 v0, 0
	s_addc_u32 s82, s59, 0
	s_mov_b32 s83, -2
	s_waitcnt lgkmcnt(0)
	v_mov_b32_e32 v1, v0
	v_mov_b32_e32 v2, v0
	v_mov_b32_e32 v3, v0
	v_mov_b32_e32 v4, v0
	v_mov_b32_e32 v5, v0
	v_mov_b32_e32 v6, v0
	v_mov_b32_e32 v7, v0
	v_mov_b32_e32 v16, v0
	v_mov_b32_e32 v17, v0
	v_mov_b32_e32 v18, v0
	v_mov_b32_e32 v19, v0
	v_mov_b32_e32 v20, v0
	v_mov_b32_e32 v21, v0
	v_mov_b32_e32 v22, v0
	v_mov_b32_e32 v23, v0
	v_mov_b32_e32 v32, v0
	v_mov_b32_e32 v33, v0
	v_mov_b32_e32 v34, v0
	v_mov_b32_e32 v35, v0
	s_waitcnt vmcnt(0)
	v_mov_b64_e32 v[8:9], 0
	v_mov_b64_e32 v[10:11], 0
	v_mov_b64_e32 v[12:13], 0
	v_mov_b32_e32 v14, 0
	s_nop 0
	s_nop 0
	s_nop 0
	s_nop 0
	s_nop 0
	s_nop 0
	s_nop 0
	s_nop 0
	s_nop 0
	s_nop 0
	s_nop 0
	s_nop 0

.LBB0_965:
	s_add_u32 s12, s28, 0x4300000
	s_addc_u32 s13, s29, 0
	s_add_u32 s14, s28, 0x9b00000
	s_addc_u32 s15, s29, 0
	s_lshl_b32 s0, s18, 5
	s_mov_b64 s[18:19], 0x80
	s_and_b32 s3, s0, 0x60
	s_add_i32 m0, s53, 0x18000
	v_lshl_add_u64 v[6:7], v[6:7], 0, s[18:19]
	s_lshl_b32 s2, s37, 13
	s_lshl_b32 s38, s3, 7
	v_mov_b64_e32 v[14:15], 0
	v_mov_b64_e32 v[16:17], 0
	v_mov_b64_e32 v[18:19], 0
	v_mov_b64_e32 v[20:21], 0
	v_mov_b64_e32 v[22:23], 0
	v_mov_b64_e32 v[24:25], 0
	v_mov_b64_e32 v[26:27], 0
	v_mov_b64_e32 v[28:29], 0
	v_mov_b64_e32 v[30:31], 0
	v_mov_b64_e32 v[32:33], 0
	v_mov_b64_e32 v[34:35], 0
	v_mov_b64_e32 v[36:37], 0
	v_mov_b32_e32 v39, 0
	v_mov_b64_e32 v[40:41], 0
	v_mov_b64_e32 v[42:43], 0
	v_mov_b64_e32 v[44:45], 0
	v_mov_b64_e32 v[46:47], 0
	v_mov_b64_e32 v[48:49], 0
	v_mov_b64_e32 v[50:51], 0
	v_mov_b64_e32 v[52:53], 0
	v_mov_b64_e32 v[54:55], 0
	v_mov_b64_e32 v[56:57], 0
	v_mov_b64_e32 v[58:59], 0
	v_mov_b64_e32 v[60:61], 0
	v_mov_b64_e32 v[62:63], 0
	v_mov_b64_e32 v[64:65], 0
	v_mov_b64_e32 v[66:67], 0
	v_mov_b64_e32 v[68:69], 0
	v_mov_b64_e32 v[70:71], 0
	v_mov_b64_e32 v[72:73], 0
	v_mov_b64_e32 v[74:75], 0
	v_mov_b64_e32 v[76:77], 0
	v_mov_b64_e32 v[78:79], 0
	v_mov_b64_e32 v[80:81], 0
	v_mov_b64_e32 v[82:83], 0
	v_mov_b64_e32 v[84:85], 0
	v_mov_b64_e32 v[86:87], 0
	v_mov_b64_e32 v[88:89], 0
	v_mov_b64_e32 v[90:91], 0
	v_mov_b64_e32 v[92:93], 0
	v_mov_b64_e32 v[94:95], 0
	v_mov_b64_e32 v[96:97], 0
	v_mov_b64_e32 v[98:99], 0
	v_mov_b64_e32 v[100:101], 0
	v_mov_b64_e32 v[102:103], 0
	v_mov_b64_e32 v[104:105], 0
	v_mov_b64_e32 v[106:107], 0
	v_mov_b64_e32 v[108:109], 0
	v_mov_b64_e32 v[110:111], 0
	v_mov_b64_e32 v[112:113], 0
	v_mov_b64_e32 v[114:115], 0
	v_mov_b64_e32 v[116:117], 0
	v_mov_b64_e32 v[118:119], 0
	v_mov_b64_e32 v[124:125], 0
	v_mov_b64_e32 v[126:127], 0
	v_mov_b64_e32 v[132:133], 0
	v_mov_b64_e32 v[134:135], 0
	s_waitcnt vmcnt(2)
	s_barrier
	global_load_lds_dwordx4 v[6:7], off
	v_lshl_add_u64 v[4:5], v[4:5], 0, s[18:19]
	s_add_i32 m0, s53, 0x1a000
	s_add_i32 s58, s53, 0x8000
	s_add_i32 s59, s53, 0xa000
	global_load_lds_dwordx4 v[4:5], off
	v_lshl_add_u64 v[0:1], v[0:1], 0, s[18:19]
	s_mov_b32 m0, s58
	s_add_u32 s0, s6, 0x40080
	global_load_lds_dwordx4 v[0:1], off
	v_lshl_add_u64 v[0:1], v[2:3], 0, s[18:19]
	s_mov_b32 m0, s59
	s_addc_u32 s1, s7, 0
	global_load_lds_dwordx4 v[0:1], off
	s_add_i32 m0, s53, 0x1c000
	v_lshl_add_u64 v[0:1], s[0:1], 0, v[182:183]
	global_load_lds_dwordx4 v[0:1], off
	v_lshl_add_u64 v[0:1], s[0:1], 0, v[186:187]
	s_add_i32 m0, s53, 0x1e000
	v_bfe_u32 v2, v38, 4, 2
	global_load_lds_dwordx4 v[0:1], off
	v_and_b32_e32 v1, 15, v38
	v_lshlrev_b32_e32 v0, 4, v2
	v_lshl_or_b32 v234, s37, 6, v1
	v_lshl_or_b32 v3, v1, 6, v0
	v_cmp_lt_u32_e64 s[0:1], 13, v1
	v_mov_b32_e32 v1, v183
	v_lshl_add_u64 v[188:189], s[74:75], 0, v[0:1]
	v_lshlrev_b32_e32 v0, 14, v8
	v_and_b32_e32 v0, 0xffff8000, v0
	v_lshl_add_u32 v0, v9, 11, v0
	v_and_b32_e32 v1, 1, v8
	v_lshlrev_b32_e32 v4, 2, v38
	s_cmpk_lt_u32 s36, 0x100
	v_lshl_or_b32 v0, v1, 6, v0
	v_and_b32_e32 v4, 32, v4
	s_cselect_b64 s[36:37], -1, 0
	s_ashr_i32 s61, s17, 31
	s_ashr_i32 s63, s16, 31
	v_lshl_add_u32 v190, v10, 1, v0
	v_lshlrev_b32_e32 v0, 14, v11
	v_bitop3_b32 v235, s38, v3, v4 bitop3:0xf6
	s_add_u32 s38, s20, 0x2c00
	v_and_b32_e32 v0, 0xffff8000, v0
	s_addc_u32 s39, s21, 0
	v_lshl_add_u32 v0, v12, 11, v0
	v_and_b32_e32 v1, 1, v11
	s_waitcnt vmcnt(6)
	s_add_u32 s44, s20, 0x5800
	v_lshl_or_b32 v0, v1, 6, v0
	v_bitop3_b32 v5, v3, s2, v4 bitop3:0xde
	s_addc_u32 s45, s21, 0
	v_lshl_add_u32 v192, v13, 1, v0
	s_add_i32 s68, 0, 0x10000
	s_add_i32 s69, 0, 0x14000
	v_mbcnt_lo_u32_b32 v0, -1, 0
	v_lshl_or_b32 v236, v2, 3, s3
	v_mov_b32_e32 v191, v183
	v_mov_b32_e32 v193, v183
	v_mov_b64_e32 v[194:195], 0x2c0
	v_mov_b64_e32 v[196:197], 0x2bf
	v_add_u32_e32 v237, s68, v235
	v_add_u32_e32 v238, s69, v235
	v_add_u32_e32 v239, 0, v5
	v_mbcnt_hi_u32_b32 v240, -1, v0
	s_movk_i32 s70, 0x1600
	v_mov_b32_e32 v241, 0x358637bd
	s_mov_b32 s60, 0x3a800000
	s_mov_b32 s77, 0x800000
	s_mov_b32 s62, 0x358637bd
	s_barrier
	s_branch .LBB0_968

.LBB0_967:
	s_andn2_b64 vcc, exec, s[2:3]
	s_mov_b32 s71, s84
	s_mov_b32 s72, s85
	s_mov_b64 s[6:7], s[80:81]
	s_mov_b64 s[4:5], s[78:79]
	s_cbranch_vccz .LBB0_1001
	v_mov_b64_e32 v[14:15], 0
	v_mov_b64_e32 v[16:17], 0
	v_mov_b64_e32 v[18:19], 0
	v_mov_b64_e32 v[20:21], 0
	v_mov_b64_e32 v[22:23], 0
	v_mov_b64_e32 v[24:25], 0
	v_mov_b64_e32 v[26:27], 0
	v_mov_b64_e32 v[28:29], 0
	v_mov_b64_e32 v[30:31], 0
	v_mov_b64_e32 v[32:33], 0
	v_mov_b64_e32 v[34:35], 0
	v_mov_b64_e32 v[36:37], 0
	v_mov_b32_e32 v39, 0
	v_mov_b64_e32 v[40:41], 0
	v_mov_b64_e32 v[42:43], 0
	v_mov_b64_e32 v[44:45], 0
	v_mov_b64_e32 v[46:47], 0
	v_mov_b64_e32 v[48:49], 0
	v_mov_b64_e32 v[50:51], 0
	v_mov_b64_e32 v[52:53], 0
	v_mov_b64_e32 v[54:55], 0
	v_mov_b64_e32 v[56:57], 0
	v_mov_b64_e32 v[58:59], 0
	v_mov_b64_e32 v[60:61], 0
	v_mov_b64_e32 v[62:63], 0
	v_mov_b64_e32 v[64:65], 0
	v_mov_b64_e32 v[66:67], 0
	v_mov_b64_e32 v[68:69], 0
	v_mov_b64_e32 v[70:71], 0
	v_mov_b64_e32 v[72:73], 0
	v_mov_b64_e32 v[74:75], 0
	v_mov_b64_e32 v[76:77], 0
	v_mov_b64_e32 v[78:79], 0
	v_mov_b64_e32 v[80:81], 0
	v_mov_b64_e32 v[82:83], 0
	v_mov_b64_e32 v[84:85], 0
	v_mov_b64_e32 v[86:87], 0
	v_mov_b64_e32 v[88:89], 0
	v_mov_b64_e32 v[90:91], 0
	v_mov_b64_e32 v[92:93], 0
	v_mov_b64_e32 v[94:95], 0
	v_mov_b64_e32 v[96:97], 0
	v_mov_b64_e32 v[98:99], 0
	v_mov_b64_e32 v[100:101], 0
	v_mov_b64_e32 v[102:103], 0
	v_mov_b64_e32 v[104:105], 0
	v_mov_b64_e32 v[106:107], 0
	v_mov_b64_e32 v[108:109], 0
	v_mov_b64_e32 v[110:111], 0
	v_mov_b64_e32 v[112:113], 0
	v_mov_b64_e32 v[114:115], 0
	v_mov_b64_e32 v[116:117], 0
	v_mov_b64_e32 v[118:119], 0
	v_mov_b64_e32 v[124:125], 0
	v_mov_b64_e32 v[126:127], 0
	v_mov_b64_e32 v[132:133], 0
	v_mov_b64_e32 v[134:135], 0

.LBB0_970:
	s_ashr_i32 s65, s64, 31
	s_lshl_b64 s[78:79], s[64:65], 11
	s_add_u32 s78, s34, s78
	s_addc_u32 s79, s35, s79
	s_and_b64 s[80:81], s[2:3], exec
	s_cselect_b32 s65, s79, s5
	s_cselect_b32 s73, s78, s4
	s_ashr_i32 s67, s66, 31
	s_lshl_b64 s[80:81], s[66:67], 11
	s_add_u32 s80, s40, s80
	s_addc_u32 s81, s41, s81
	s_and_b64 s[82:83], s[2:3], exec
	s_cselect_b32 s67, s81, s7
	s_cselect_b32 s76, s80, s6
	s_add_u32 s4, s4, 0x40080
	s_addc_u32 s5, s5, 0
	s_add_u32 s86, s6, 0x100
	v_mov_b32_e32 v0, 0
	s_addc_u32 s87, s7, 0
	s_mov_b32 s88, -2
	v_mov_b32_e32 v1, 0
	v_mov_b64_e32 v[2:3], 0
	v_mov_b64_e32 v[4:5], 0
	v_mov_b64_e32 v[6:7], 0
	v_mov_b64_e32 v[8:9], 0
	v_mov_b64_e32 v[10:11], 0
	v_mov_b64_e32 v[12:13], 0
	v_mov_b32_e32 v38, 0
	s_nop 0
	s_nop 0
	s_nop 0
	s_nop 0
	s_nop 0
	s_nop 0

.LBB0_1067:
	s_mov_b64 s[14:15], 0x80
	s_and_b32 s58, s4, 3
	s_add_i32 m0, s54, 0x18000
	v_lshl_add_u64 v[8:9], v[8:9], 0, s[14:15]
	s_lshl_b32 s1, s0, 13
	s_lshl_b32 s4, s58, 12
	v_mov_b64_e32 v[10:11], 0
	v_mov_b64_e32 v[12:13], 0
	v_mov_b64_e32 v[14:15], 0
	v_mov_b64_e32 v[16:17], 0
	v_mov_b64_e32 v[18:19], 0
	v_mov_b64_e32 v[20:21], 0
	v_mov_b64_e32 v[22:23], 0
	v_mov_b64_e32 v[24:25], 0
	v_mov_b64_e32 v[26:27], 0
	v_mov_b64_e32 v[28:29], 0
	v_mov_b64_e32 v[30:31], 0
	v_mov_b64_e32 v[32:33], 0
	v_mov_b64_e32 v[34:35], 0
	v_mov_b64_e32 v[46:47], 0
	v_mov_b64_e32 v[48:49], 0
	v_mov_b64_e32 v[50:51], 0
	v_mov_b64_e32 v[52:53], 0
	v_mov_b64_e32 v[54:55], 0
	v_mov_b64_e32 v[56:57], 0
	v_mov_b64_e32 v[58:59], 0
	v_mov_b64_e32 v[60:61], 0
	v_mov_b64_e32 v[62:63], 0
	v_mov_b64_e32 v[64:65], 0
	v_mov_b64_e32 v[66:67], 0
	v_mov_b64_e32 v[68:69], 0
	v_mov_b64_e32 v[70:71], 0
	v_mov_b64_e32 v[72:73], 0
	v_mov_b64_e32 v[74:75], 0
	v_mov_b64_e32 v[76:77], 0
	v_mov_b64_e32 v[78:79], 0
	v_mov_b64_e32 v[80:81], 0
	v_mov_b64_e32 v[82:83], 0
	v_mov_b64_e32 v[84:85], 0
	v_mov_b64_e32 v[86:87], 0
	v_mov_b64_e32 v[88:89], 0
	v_mov_b64_e32 v[90:91], 0
	v_mov_b64_e32 v[92:93], 0
	v_mov_b64_e32 v[94:95], 0
	v_mov_b64_e32 v[96:97], 0
	v_mov_b64_e32 v[98:99], 0
	v_mov_b64_e32 v[100:101], 0
	v_mov_b64_e32 v[102:103], 0
	v_mov_b64_e32 v[104:105], 0
	v_mov_b64_e32 v[106:107], 0
	v_mov_b64_e32 v[108:109], 0
	v_mov_b64_e32 v[110:111], 0
	v_mov_b64_e32 v[112:113], 0
	v_mov_b64_e32 v[114:115], 0
	v_mov_b64_e32 v[116:117], 0
	v_mov_b64_e32 v[118:119], 0
	v_mov_b64_e32 v[120:121], 0
	v_mov_b64_e32 v[122:123], 0
	v_mov_b64_e32 v[124:125], 0
	v_mov_b64_e32 v[126:127], 0
	s_waitcnt vmcnt(2)
	s_barrier
	global_load_lds_dwordx4 v[8:9], off
	v_lshl_add_u64 v[6:7], v[6:7], 0, s[14:15]
	s_add_i32 m0, s54, 0x1a000
	s_add_i32 s59, s54, 0x8000
	s_add_i32 s62, s54, 0xa000
	global_load_lds_dwordx4 v[6:7], off
	v_lshl_add_u64 v[2:3], v[2:3], 0, s[14:15]
	s_mov_b32 m0, s59
	s_add_u32 s2, s38, 0xb0080
	global_load_lds_dwordx4 v[2:3], off
	v_lshl_add_u64 v[2:3], v[4:5], 0, s[14:15]
	s_mov_b32 m0, s62
	s_addc_u32 s3, s39, 0
	global_load_lds_dwordx4 v[2:3], off
	s_add_i32 m0, s54, 0x1c000
	v_lshl_add_u64 v[2:3], s[2:3], 0, v[154:155]
	global_load_lds_dwordx4 v[2:3], off
	v_lshl_add_u64 v[2:3], s[2:3], 0, v[158:159]
	s_add_i32 m0, s54, 0x1e000
	v_bfe_u32 v1, v36, 4, 2
	global_load_lds_dwordx4 v[2:3], off
	v_lshlrev_b32_e32 v3, 4, v1
	v_lshl_or_b32 v3, v45, 6, v3
	v_and_b32_e32 v0, 32, v0
	s_movk_i32 s6, 0xb00
	v_lshl_or_b32 v184, s0, 6, v45
	v_lshlrev_b32_e32 v2, 3, v1
	v_bitop3_b32 v4, v3, s1, v0 bitop3:0xde
	v_bitop3_b32 v185, v3, s4, v0 bitop3:0xde
	v_cmp_eq_u32_e64 s[0:1], 0, v1
	v_lshrrev_b32_e32 v1, 1, v37
	v_mul_lo_u32 v0, v39, s6
	s_mov_b32 s7, 0xb000
	v_mad_u64_u32 v[0:1], s[4:5], v1, s7, v[0:1]
	v_or_b32_e32 v0, v0, v38
	s_mov_b64 s[2:3], 0xb0080
	v_add_lshl_u32 v0, v0, v40, 1
	v_mov_b32_e32 v1, 0
	v_lshl_or_b32 v186, s58, 5, v2
	v_lshl_add_u64 v[160:161], v[0:1], 0, s[2:3]
	v_lshrrev_b32_e32 v2, 1, v41
	v_mul_lo_u32 v0, v42, s6
	v_mad_u64_u32 v[2:3], s[4:5], v2, s7, v[0:1]
	v_or_b32_e32 v0, v2, v43
	s_waitcnt vmcnt(6)
	v_add_lshl_u32 v0, v0, v44, 1
	v_lshl_add_u64 v[162:163], v[0:1], 0, s[2:3]
	s_add_i32 s65, 0, 0x10000
	s_add_i32 s66, 0, 0x14000
	v_mbcnt_lo_u32_b32 v0, -1, 0
	s_mov_b32 s19, 0
	s_ashr_i32 s63, s17, 31
	s_ashr_i32 s64, s16, 31
	v_mov_b64_e32 v[164:165], 0x100
	v_mov_b64_e32 v[166:167], 0xff
	v_add_u32_e32 v187, s65, v185
	v_add_u32_e32 v188, s66, v185
	v_add_u32_e32 v189, 0, v4
	v_mbcnt_hi_u32_b32 v190, -1, v0
	s_mov_b32 s67, 0
	s_barrier
	s_branch .LBB0_1069
.LBB0_1068:
	s_or_b64 exec, exec, s[38:39]
	s_and_b64 vcc, exec, s[2:3]
	s_mov_b32 s18, s68
	s_mov_b32 s72, s71
	s_mov_b64 s[38:39], s[6:7]
	s_mov_b64 s[36:37], s[4:5]
	s_cbranch_vccnz .LBB0_1097
	v_mov_b64_e32 v[10:11], 0
	v_mov_b64_e32 v[12:13], 0
	v_mov_b64_e32 v[14:15], 0
	v_mov_b64_e32 v[16:17], 0
	v_mov_b64_e32 v[18:19], 0
	v_mov_b64_e32 v[20:21], 0
	v_mov_b64_e32 v[22:23], 0
	v_mov_b64_e32 v[24:25], 0
	v_mov_b64_e32 v[26:27], 0
	v_mov_b64_e32 v[28:29], 0
	v_mov_b64_e32 v[30:31], 0
	v_mov_b64_e32 v[32:33], 0
	v_mov_b64_e32 v[34:35], 0
	v_mov_b64_e32 v[46:47], 0
	v_mov_b64_e32 v[48:49], 0
	v_mov_b64_e32 v[50:51], 0
	v_mov_b64_e32 v[52:53], 0
	v_mov_b64_e32 v[54:55], 0
	v_mov_b64_e32 v[56:57], 0
	v_mov_b64_e32 v[58:59], 0
	v_mov_b64_e32 v[60:61], 0
	v_mov_b64_e32 v[62:63], 0
	v_mov_b64_e32 v[64:65], 0
	v_mov_b64_e32 v[66:67], 0
	v_mov_b64_e32 v[68:69], 0
	v_mov_b64_e32 v[70:71], 0
	v_mov_b64_e32 v[72:73], 0
	v_mov_b64_e32 v[74:75], 0
	v_mov_b64_e32 v[76:77], 0
	v_mov_b64_e32 v[78:79], 0
	v_mov_b64_e32 v[80:81], 0
	v_mov_b64_e32 v[82:83], 0
	v_mov_b64_e32 v[84:85], 0
	v_mov_b64_e32 v[86:87], 0
	v_mov_b64_e32 v[88:89], 0
	v_mov_b64_e32 v[90:91], 0
	v_mov_b64_e32 v[92:93], 0
	v_mov_b64_e32 v[94:95], 0
	v_mov_b64_e32 v[96:97], 0
	v_mov_b64_e32 v[98:99], 0
	v_mov_b64_e32 v[100:101], 0
	v_mov_b64_e32 v[102:103], 0
	v_mov_b64_e32 v[104:105], 0
	v_mov_b64_e32 v[106:107], 0
	v_mov_b64_e32 v[108:109], 0
	v_mov_b64_e32 v[110:111], 0
	v_mov_b64_e32 v[112:113], 0
	v_mov_b64_e32 v[114:115], 0
	v_mov_b64_e32 v[116:117], 0
	v_mov_b64_e32 v[118:119], 0
	v_mov_b64_e32 v[120:121], 0
	v_mov_b64_e32 v[122:123], 0
	v_mov_b64_e32 v[124:125], 0
	v_mov_b64_e32 v[126:127], 0

.LBB0_1079:
	s_add_u32 s73, s38, 0x100
	v_mov_b32_e32 v0, 0
	s_addc_u32 s76, s39, 0
	s_mov_b32 s77, -2
	s_waitcnt lgkmcnt(0)
	v_mov_b32_e32 v1, 0
	v_mov_b64_e32 v[2:3], 0
	v_mov_b64_e32 v[4:5], 0
	v_mov_b64_e32 v[6:7], 0
	v_mov_b64_e32 v[8:9], 0
	v_mov_b64_e32 v[36:37], 0
	v_mov_b64_e32 v[38:39], 0
	v_mov_b64_e32 v[40:41], 0
	v_mov_b64_e32 v[42:43], 0
	v_mov_b64_e32 v[44:45], 0
	s_nop 0
	s_nop 0
	s_nop 0
	s_nop 0
	s_nop 0
	s_nop 0
	s_nop 0
	s_nop 0
	s_nop 0
	s_nop 0

.LBB0_1171:
	s_lshl_b32 s1, s1, 5
	s_and_b32 s1, s1, 0x60
	s_lshl_b32 s15, s0, 13
	s_lshl_b32 s18, s1, 7
	s_add_u32 s84, s28, 0x4300000
	s_addc_u32 s85, s29, 0
	s_add_u32 s8, s28, 0xa300000
	s_addc_u32 s9, s29, 0
	s_add_u32 s10, s28, 0x578000
	s_mov_b64 s[12:13], 0x80
	s_addc_u32 s11, s29, 0
	s_add_i32 m0, s79, 0x18000
	v_lshl_add_u64 v[8:9], v[8:9], 0, s[12:13]
	v_mov_b32_e32 v15, 0
	v_mov_b64_e32 v[16:17], 0
	v_mov_b64_e32 v[18:19], 0
	v_mov_b64_e32 v[20:21], 0
	v_mov_b64_e32 v[22:23], 0
	v_mov_b64_e32 v[24:25], 0
	v_mov_b64_e32 v[28:29], 0
	v_mov_b64_e32 v[30:31], 0
	v_mov_b64_e32 v[32:33], 0
	v_mov_b64_e32 v[34:35], 0
	v_mov_b64_e32 v[36:37], 0
	v_mov_b64_e32 v[38:39], 0
	v_mov_b64_e32 v[40:41], 0
	v_mov_b64_e32 v[42:43], 0
	v_mov_b64_e32 v[44:45], 0
	v_mov_b64_e32 v[46:47], 0
	v_mov_b64_e32 v[48:49], 0
	v_mov_b64_e32 v[50:51], 0
	v_mov_b64_e32 v[52:53], 0
	v_mov_b64_e32 v[54:55], 0
	v_mov_b64_e32 v[56:57], 0
	v_mov_b64_e32 v[58:59], 0
	v_mov_b64_e32 v[60:61], 0
	v_mov_b64_e32 v[62:63], 0
	v_mov_b64_e32 v[64:65], 0
	v_mov_b64_e32 v[66:67], 0
	v_mov_b64_e32 v[68:69], 0
	v_mov_b64_e32 v[70:71], 0
	v_mov_b64_e32 v[72:73], 0
	v_mov_b64_e32 v[74:75], 0
	v_mov_b64_e32 v[76:77], 0
	v_mov_b64_e32 v[78:79], 0
	v_mov_b64_e32 v[80:81], 0
	v_mov_b64_e32 v[82:83], 0
	v_mov_b64_e32 v[84:85], 0
	v_mov_b64_e32 v[86:87], 0
	v_mov_b64_e32 v[88:89], 0
	v_mov_b64_e32 v[90:91], 0
	v_mov_b64_e32 v[92:93], 0
	v_mov_b64_e32 v[94:95], 0
	v_mov_b64_e32 v[96:97], 0
	v_mov_b64_e32 v[98:99], 0
	v_mov_b64_e32 v[100:101], 0
	v_mov_b64_e32 v[102:103], 0
	v_mov_b64_e32 v[104:105], 0
	v_mov_b64_e32 v[106:107], 0
	v_mov_b64_e32 v[108:109], 0
	v_mov_b64_e32 v[110:111], 0
	v_mov_b64_e32 v[112:113], 0
	v_mov_b64_e32 v[114:115], 0
	v_mov_b64_e32 v[116:117], 0
	v_mov_b64_e32 v[118:119], 0
	v_mov_b64_e32 v[120:121], 0
	v_mov_b64_e32 v[122:123], 0
	v_mov_b64_e32 v[124:125], 0
	v_mov_b64_e32 v[126:127], 0
	s_waitcnt vmcnt(2)
	s_barrier
	global_load_lds_dwordx4 v[8:9], off
	v_lshl_add_u64 v[6:7], v[6:7], 0, s[12:13]
	s_add_i32 m0, s79, 0x1a000
	s_add_i32 s86, s79, 0x8000
	s_add_i32 s87, s79, 0xa000
	global_load_lds_dwordx4 v[6:7], off
	v_lshl_add_u64 v[0:1], v[0:1], 0, s[12:13]
	s_mov_b32 m0, s86
	s_add_u32 s36, s62, 0x40080
	global_load_lds_dwordx4 v[0:1], off
	v_lshl_add_u64 v[0:1], v[2:3], 0, s[12:13]
	s_mov_b32 m0, s87
	s_addc_u32 s37, s63, 0
	global_load_lds_dwordx4 v[0:1], off
	s_add_i32 m0, s79, 0x1c000
	v_lshl_add_u64 v[0:1], s[36:37], 0, v[134:135]
	global_load_lds_dwordx4 v[0:1], off
	v_lshl_add_u64 v[0:1], s[36:37], 0, v[138:139]
	s_add_i32 m0, s79, 0x1e000
	v_and_b32_e32 v2, 32, v4
	global_load_lds_dwordx4 v[0:1], off
	v_bfe_u32 v0, v26, 4, 2
	v_lshlrev_b32_e32 v140, 4, v0
	v_lshl_or_b32 v174, v0, 3, s1
	v_lshlrev_b32_e32 v0, 14, v5
	v_lshl_or_b32 v1, v27, 6, v140
	v_and_b32_e32 v0, 0xffff8000, v0
	v_bitop3_b32 v3, v1, s15, v2 bitop3:0xde
	v_bitop3_b32 v173, s18, v1, v2 bitop3:0xf6
	v_lshl_add_u32 v0, v10, 11, v0
	v_and_b32_e32 v1, 1, v5
	v_lshl_or_b32 v0, v1, 6, v0
	v_lshl_add_u32 v144, v11, 1, v0
	v_lshlrev_b32_e32 v0, 14, v12
	v_and_b32_e32 v0, 0xffff8000, v0
	v_lshl_add_u32 v0, v13, 11, v0
	v_and_b32_e32 v1, 1, v12
	s_waitcnt vmcnt(6)
	s_cmpk_lt_u32 s14, 0x100
	v_lshl_or_b32 v0, v1, 6, v0
	s_cselect_b64 s[14:15], -1, 0
	v_lshl_add_u32 v146, v14, 1, v0
	s_add_i32 s89, 0, 0x10000
	s_add_i32 s90, 0, 0x14000
	v_mbcnt_lo_u32_b32 v0, -1, 0
	v_lshl_or_b32 v172, s0, 6, v27
	s_ashr_i32 s88, s17, 31
	v_lshl_add_u64 v[142:143], s[74:75], 0, v[140:141]
	v_mov_b32_e32 v145, v141
	v_mov_b32_e32 v147, v141
	v_mov_b64_e32 v[148:149], 0x400
	v_mov_b64_e32 v[150:151], 0x3ff
	v_add_u32_e32 v175, s89, v173
	v_add_u32_e32 v176, s90, v173
	v_add_u32_e32 v177, 0, v3
	v_mbcnt_hi_u32_b32 v178, -1, v0
	s_mov_b32 s18, 0x3a800000
	s_mov_b32 s91, 0x800000
	s_mov_b32 s92, 0x3f317217
	s_mov_b32 s93, 0x7f800000
	v_mov_b32_e32 v179, 0x41b17218
	s_barrier
	s_branch .LBB0_1174

.LBB0_1173:
	s_andn2_b64 vcc, exec, s[0:1]
	s_mov_b32 s40, s94
	s_mov_b32 s41, s95
	s_mov_b64 s[62:63], s[60:61]
	s_mov_b64 s[2:3], s[44:45]
	s_cbranch_vccz .LBB0_1191
	v_mov_b32_e32 v15, 0
	v_mov_b64_e32 v[16:17], 0
	v_mov_b64_e32 v[18:19], 0
	v_mov_b64_e32 v[20:21], 0
	v_mov_b64_e32 v[22:23], 0
	v_mov_b64_e32 v[24:25], 0
	v_mov_b64_e32 v[28:29], 0
	v_mov_b64_e32 v[30:31], 0
	v_mov_b64_e32 v[32:33], 0
	v_mov_b64_e32 v[34:35], 0
	v_mov_b64_e32 v[36:37], 0
	v_mov_b64_e32 v[38:39], 0
	v_mov_b64_e32 v[40:41], 0
	v_mov_b64_e32 v[42:43], 0
	v_mov_b64_e32 v[44:45], 0
	v_mov_b64_e32 v[46:47], 0
	v_mov_b64_e32 v[48:49], 0
	v_mov_b64_e32 v[50:51], 0
	v_mov_b64_e32 v[52:53], 0
	v_mov_b64_e32 v[54:55], 0
	v_mov_b64_e32 v[56:57], 0
	v_mov_b64_e32 v[58:59], 0
	v_mov_b64_e32 v[60:61], 0
	v_mov_b64_e32 v[62:63], 0
	v_mov_b64_e32 v[64:65], 0
	v_mov_b64_e32 v[66:67], 0
	v_mov_b64_e32 v[68:69], 0
	v_mov_b64_e32 v[70:71], 0
	v_mov_b64_e32 v[72:73], 0
	v_mov_b64_e32 v[74:75], 0
	v_mov_b64_e32 v[76:77], 0
	v_mov_b64_e32 v[78:79], 0
	v_mov_b64_e32 v[80:81], 0
	v_mov_b64_e32 v[82:83], 0
	v_mov_b64_e32 v[84:85], 0
	v_mov_b64_e32 v[86:87], 0
	v_mov_b64_e32 v[88:89], 0
	v_mov_b64_e32 v[90:91], 0
	v_mov_b64_e32 v[92:93], 0
	v_mov_b64_e32 v[94:95], 0
	v_mov_b64_e32 v[96:97], 0
	v_mov_b64_e32 v[98:99], 0
	v_mov_b64_e32 v[100:101], 0
	v_mov_b64_e32 v[102:103], 0
	v_mov_b64_e32 v[104:105], 0
	v_mov_b64_e32 v[106:107], 0
	v_mov_b64_e32 v[108:109], 0
	v_mov_b64_e32 v[110:111], 0
	v_mov_b64_e32 v[112:113], 0
	v_mov_b64_e32 v[114:115], 0
	v_mov_b64_e32 v[116:117], 0
	v_mov_b64_e32 v[118:119], 0
	v_mov_b64_e32 v[120:121], 0
	v_mov_b64_e32 v[122:123], 0
	v_mov_b64_e32 v[124:125], 0
	v_mov_b64_e32 v[126:127], 0

.LBB0_1180:
	s_ashr_i32 s37, s36, 31
	s_lshl_b64 s[44:45], s[36:37], 11
	s_add_u32 s44, s34, s44
	s_addc_u32 s45, s35, s45
	s_and_b64 s[52:53], s[0:1], exec
	s_cselect_b32 s37, s45, s3
	s_cselect_b32 s52, s44, s2
	s_ashr_i32 s39, s38, 31
	s_lshl_b64 s[54:55], s[38:39], 11
	s_add_u32 s60, s67, s54
	s_addc_u32 s61, s78, s55
	s_and_b64 s[54:55], s[0:1], exec
	s_cselect_b32 s39, s61, s63
	s_cselect_b32 s53, s60, s62
	s_add_u32 s2, s2, 0x40080
	s_addc_u32 s3, s3, 0
	s_add_u32 s54, s62, 0x100
	v_mov_b32_e32 v0, 0
	s_addc_u32 s55, s63, 0
	s_mov_b32 s56, -2
	v_mov_b32_e32 v1, 0
	v_mov_b64_e32 v[2:3], 0
	v_mov_b64_e32 v[4:5], 0
	v_mov_b64_e32 v[6:7], 0
	v_mov_b64_e32 v[8:9], 0
	v_mov_b64_e32 v[10:11], 0
	v_mov_b64_e32 v[12:13], 0
	v_mov_b32_e32 v14, 0
	v_mov_b64_e32 v[26:27], 0
	s_nop 0
	s_nop 0
	s_nop 0
	s_nop 0
	s_nop 0
	s_nop 0
	s_nop 0

.LBB0_1521:
	s_mov_b64 s[6:7], 0x80
	s_and_b32 s50, s9, 3
	s_add_i32 m0, s46, 0x18000
	v_lshl_add_u64 v[8:9], v[8:9], 0, s[6:7]
	s_lshl_b32 s1, s0, 13
	s_lshl_b32 s9, s50, 12
	v_mov_b64_e32 v[10:11], 0
	v_mov_b64_e32 v[12:13], 0
	v_mov_b64_e32 v[14:15], 0
	v_mov_b64_e32 v[36:37], 0
	v_mov_b64_e32 v[38:39], 0
	v_mov_b64_e32 v[40:41], 0
	v_mov_b64_e32 v[42:43], 0
	v_mov_b64_e32 v[44:45], 0
	v_mov_b64_e32 v[46:47], 0
	v_mov_b64_e32 v[48:49], 0
	v_mov_b64_e32 v[50:51], 0
	v_mov_b64_e32 v[52:53], 0
	v_mov_b64_e32 v[54:55], 0
	v_mov_b64_e32 v[56:57], 0
	v_mov_b64_e32 v[58:59], 0
	v_mov_b64_e32 v[60:61], 0
	v_mov_b64_e32 v[62:63], 0
	v_mov_b64_e32 v[64:65], 0
	v_mov_b64_e32 v[66:67], 0
	v_mov_b64_e32 v[68:69], 0
	v_mov_b64_e32 v[70:71], 0
	v_mov_b64_e32 v[72:73], 0
	v_mov_b64_e32 v[74:75], 0
	v_mov_b64_e32 v[76:77], 0
	v_mov_b64_e32 v[78:79], 0
	v_mov_b64_e32 v[80:81], 0
	v_mov_b64_e32 v[82:83], 0
	v_mov_b64_e32 v[84:85], 0
	v_mov_b64_e32 v[86:87], 0
	v_mov_b64_e32 v[88:89], 0
	v_mov_b64_e32 v[90:91], 0
	v_mov_b64_e32 v[92:93], 0
	v_mov_b64_e32 v[94:95], 0
	v_mov_b64_e32 v[96:97], 0
	v_mov_b64_e32 v[98:99], 0
	v_mov_b64_e32 v[100:101], 0
	v_mov_b64_e32 v[102:103], 0
	v_mov_b64_e32 v[104:105], 0
	v_mov_b64_e32 v[106:107], 0
	v_mov_b64_e32 v[108:109], 0
	v_mov_b64_e32 v[110:111], 0
	v_mov_b64_e32 v[112:113], 0
	v_mov_b64_e32 v[114:115], 0
	v_mov_b64_e32 v[116:117], 0
	v_mov_b64_e32 v[118:119], 0
	v_mov_b64_e32 v[120:121], 0
	v_mov_b64_e32 v[122:123], 0
	v_mov_b64_e32 v[124:125], 0
	v_mov_b64_e32 v[126:127], 0
	s_waitcnt vmcnt(2)
	s_barrier
	global_load_lds_dwordx4 v[8:9], off
	v_lshl_add_u64 v[6:7], v[6:7], 0, s[6:7]
	s_add_i32 m0, s46, 0x1a000
	s_add_i32 s51, s46, 0x8000
	s_add_i32 s52, s46, 0xa000
	global_load_lds_dwordx4 v[6:7], off
	v_lshl_add_u64 v[0:1], v[0:1], 0, s[6:7]
	s_mov_b32 m0, s51
	s_add_u32 s2, s36, 0x40080
	global_load_lds_dwordx4 v[0:1], off
	v_lshl_add_u64 v[0:1], v[2:3], 0, s[6:7]
	s_mov_b32 m0, s52
	s_addc_u32 s3, s37, 0
	global_load_lds_dwordx4 v[0:1], off
	s_add_i32 m0, s46, 0x1c000
	v_lshl_add_u64 v[0:1], s[2:3], 0, v[154:155]
	global_load_lds_dwordx4 v[0:1], off
	v_lshl_add_u64 v[0:1], s[2:3], 0, v[158:159]
	s_add_i32 m0, s46, 0x1e000
	v_and_b32_e32 v3, 32, v4
	global_load_lds_dwordx4 v[0:1], off
	v_bfe_u32 v0, v24, 4, 2
	v_lshlrev_b32_e32 v2, 4, v0
	v_lshl_or_b32 v2, v31, 6, v2
	v_lshl_or_b32 v184, s0, 6, v31
	v_lshlrev_b32_e32 v1, 3, v0
	v_bitop3_b32 v4, v2, s1, v3 bitop3:0xde
	v_cmp_eq_u32_e64 s[0:1], 0, v0
	v_lshlrev_b32_e32 v0, 14, v25
	v_and_b32_e32 v0, 0xffff8000, v0
	v_lshl_or_b32 v186, s50, 5, v1
	v_lshl_add_u32 v0, v26, 11, v0
	v_and_b32_e32 v1, 1, v25
	v_lshl_or_b32 v0, v1, 6, v0
	v_lshl_add_u32 v160, v27, 1, v0
	v_lshlrev_b32_e32 v0, 14, v28
	v_and_b32_e32 v0, 0xffff8000, v0
	v_lshl_add_u32 v0, v29, 11, v0
	v_and_b32_e32 v1, 1, v28
	s_waitcnt vmcnt(6)
	v_lshl_or_b32 v0, v1, 6, v0
	v_bitop3_b32 v185, v2, s9, v3 bitop3:0xde
	v_mov_b32_e32 v161, 0
	v_lshl_add_u32 v162, v30, 1, v0
	s_add_i32 s55, 0, 0x10000
	s_add_i32 s56, 0, 0x14000
	v_mbcnt_lo_u32_b32 v0, -1, 0
	s_mov_b32 s9, 0
	s_ashr_i32 s53, s17, 31
	s_ashr_i32 s54, s16, 31
	v_mov_b32_e32 v163, v161
	v_mov_b64_e32 v[164:165], 0x100
	v_mov_b64_e32 v[166:167], 0xff
	v_add_u32_e32 v187, s55, v185
	v_add_u32_e32 v188, s56, v185
	v_add_u32_e32 v189, 0, v4
	v_mbcnt_hi_u32_b32 v190, -1, v0
	s_mov_b32 s57, 0
	s_barrier
	s_branch .LBB0_1523
.LBB0_1522:
	s_or_b64 exec, exec, s[36:37]
	s_and_b64 vcc, exec, s[2:3]
	s_mov_b32 s8, s58
	s_mov_b32 s60, s59
	s_mov_b64 s[36:37], s[18:19]
	s_mov_b64 s[24:25], s[14:15]
	s_cbranch_vccnz .LBB0_1547
	v_mov_b64_e32 v[10:11], 0
	v_mov_b64_e32 v[12:13], 0
	v_mov_b64_e32 v[14:15], 0
	v_mov_b64_e32 v[36:37], 0
	v_mov_b64_e32 v[38:39], 0
	v_mov_b64_e32 v[40:41], 0
	v_mov_b64_e32 v[42:43], 0
	v_mov_b64_e32 v[44:45], 0
	v_mov_b64_e32 v[46:47], 0
	v_mov_b64_e32 v[48:49], 0
	v_mov_b64_e32 v[50:51], 0
	v_mov_b64_e32 v[52:53], 0
	v_mov_b64_e32 v[54:55], 0
	v_mov_b64_e32 v[56:57], 0
	v_mov_b64_e32 v[58:59], 0
	v_mov_b64_e32 v[60:61], 0
	v_mov_b64_e32 v[62:63], 0
	v_mov_b64_e32 v[64:65], 0
	v_mov_b64_e32 v[66:67], 0
	v_mov_b64_e32 v[68:69], 0
	v_mov_b64_e32 v[70:71], 0
	v_mov_b64_e32 v[72:73], 0
	v_mov_b64_e32 v[74:75], 0
	v_mov_b64_e32 v[76:77], 0
	v_mov_b64_e32 v[78:79], 0
	v_mov_b64_e32 v[80:81], 0
	v_mov_b64_e32 v[82:83], 0
	v_mov_b64_e32 v[84:85], 0
	v_mov_b64_e32 v[86:87], 0
	v_mov_b64_e32 v[88:89], 0
	v_mov_b64_e32 v[90:91], 0
	v_mov_b64_e32 v[92:93], 0
	v_mov_b64_e32 v[94:95], 0
	v_mov_b64_e32 v[96:97], 0
	v_mov_b64_e32 v[98:99], 0
	v_mov_b64_e32 v[100:101], 0
	v_mov_b64_e32 v[102:103], 0
	v_mov_b64_e32 v[104:105], 0
	v_mov_b64_e32 v[106:107], 0
	v_mov_b64_e32 v[108:109], 0
	v_mov_b64_e32 v[110:111], 0
	v_mov_b64_e32 v[112:113], 0
	v_mov_b64_e32 v[114:115], 0
	v_mov_b64_e32 v[116:117], 0
	v_mov_b64_e32 v[118:119], 0
	v_mov_b64_e32 v[120:121], 0
	v_mov_b64_e32 v[122:123], 0
	v_mov_b64_e32 v[124:125], 0
	v_mov_b64_e32 v[126:127], 0

.LBB0_1529:
	s_ashr_i32 s11, s10, 31
	v_cmp_lt_i64_e32 vcc, s[14:15], v[164:165]
	s_lshl_b64 s[14:15], s[10:11], 11
	s_add_u32 s14, s41, s14
	s_addc_u32 s15, s42, s15
	s_and_b64 s[18:19], vcc, exec
	s_cselect_b32 s11, s15, s25
	s_cselect_b32 s61, s14, s24
	s_ashr_i32 s13, s12, 31
	s_lshl_b64 s[18:19], s[12:13], 11
	s_add_u32 s18, s43, s18
	s_addc_u32 s19, s44, s19
	s_and_b64 s[38:39], vcc, exec
	s_cselect_b32 s13, s19, s37
	s_cselect_b32 s62, s18, s36
	s_add_u32 s24, s24, 0x40080
	s_addc_u32 s25, s25, 0
	s_add_u32 s63, s36, 0x100
	v_mov_b32_e32 v0, 0
	s_addc_u32 s64, s37, 0
	s_mov_b32 s65, -2
	s_waitcnt lgkmcnt(0)
	v_mov_b32_e32 v1, v0
	v_mov_b32_e32 v2, v0
	v_mov_b32_e32 v3, v0
	v_mov_b32_e32 v4, v0
	v_mov_b32_e32 v5, v0
	v_mov_b32_e32 v6, v0
	v_mov_b32_e32 v7, v0
	v_mov_b32_e32 v16, v0
	v_mov_b32_e32 v17, v0
	v_mov_b32_e32 v18, v0
	v_mov_b32_e32 v19, v0
	v_mov_b32_e32 v20, v0
	v_mov_b32_e32 v21, v0
	v_mov_b32_e32 v22, v0
	v_mov_b32_e32 v23, v0
	v_mov_b32_e32 v32, v0
	v_mov_b32_e32 v33, v0
	v_mov_b32_e32 v34, v0
	v_mov_b32_e32 v35, v0
	s_waitcnt vmcnt(0)
	v_mov_b64_e32 v[8:9], 0
	v_mov_b64_e32 v[24:25], 0
	v_mov_b64_e32 v[26:27], 0
	v_mov_b64_e32 v[28:29], 0
	v_mov_b64_e32 v[30:31], 0
	s_nop 0
	s_nop 0
	s_nop 0
	s_nop 0
	s_nop 0
	s_nop 0
	s_nop 0
	s_nop 0
	s_nop 0
	s_nop 0
	s_nop 0
	s_nop 0
	s_nop 0
	s_nop 0
	s_nop 0

.LBB0_1869:
	s_mov_b64 s[6:7], 0x80
	s_and_b32 s2, s5, 3
	s_add_i32 m0, s39, 0x18000
	v_lshl_add_u64 v[6:7], v[6:7], 0, s[6:7]
	s_lshl_b32 s3, s8, 13
	s_lshl_b32 s5, s2, 12
	v_mov_b64_e32 v[24:25], 0
	v_mov_b64_e32 v[26:27], 0
	v_mov_b64_e32 v[28:29], 0
	v_mov_b64_e32 v[30:31], 0
	v_mov_b64_e32 v[36:37], 0
	v_mov_b64_e32 v[38:39], 0
	v_mov_b64_e32 v[40:41], 0
	v_mov_b64_e32 v[42:43], 0
	v_mov_b64_e32 v[44:45], 0
	v_mov_b64_e32 v[46:47], 0
	v_mov_b64_e32 v[48:49], 0
	v_mov_b64_e32 v[50:51], 0
	v_mov_b64_e32 v[52:53], 0
	v_mov_b64_e32 v[54:55], 0
	v_mov_b64_e32 v[56:57], 0
	v_mov_b64_e32 v[58:59], 0
	v_mov_b64_e32 v[60:61], 0
	v_mov_b64_e32 v[62:63], 0
	v_mov_b64_e32 v[64:65], 0
	v_mov_b64_e32 v[66:67], 0
	v_mov_b64_e32 v[68:69], 0
	v_mov_b64_e32 v[70:71], 0
	v_mov_b64_e32 v[72:73], 0
	v_mov_b64_e32 v[74:75], 0
	v_mov_b64_e32 v[76:77], 0
	v_mov_b64_e32 v[78:79], 0
	v_mov_b64_e32 v[80:81], 0
	v_mov_b64_e32 v[82:83], 0
	v_mov_b64_e32 v[84:85], 0
	v_mov_b64_e32 v[86:87], 0
	v_mov_b64_e32 v[88:89], 0
	v_mov_b64_e32 v[90:91], 0
	v_mov_b64_e32 v[92:93], 0
	v_mov_b64_e32 v[94:95], 0
	v_mov_b64_e32 v[96:97], 0
	v_mov_b64_e32 v[98:99], 0
	v_mov_b64_e32 v[100:101], 0
	v_mov_b64_e32 v[102:103], 0
	v_mov_b64_e32 v[104:105], 0
	v_mov_b64_e32 v[106:107], 0
	v_mov_b64_e32 v[108:109], 0
	v_mov_b64_e32 v[110:111], 0
	v_mov_b64_e32 v[112:113], 0
	v_mov_b64_e32 v[114:115], 0
	v_mov_b64_e32 v[116:117], 0
	v_mov_b64_e32 v[118:119], 0
	v_mov_b64_e32 v[120:121], 0
	v_mov_b64_e32 v[122:123], 0
	v_mov_b64_e32 v[124:125], 0
	v_mov_b64_e32 v[126:127], 0
	s_waitcnt vmcnt(2)
	s_barrier
	global_load_lds_dwordx4 v[6:7], off
	v_lshl_add_u64 v[4:5], v[4:5], 0, s[6:7]
	s_add_i32 m0, s39, 0x1a000
	s_add_i32 s44, s39, 0x8000
	s_add_i32 s45, s39, 0xa000
	global_load_lds_dwordx4 v[4:5], off
	v_lshl_add_u64 v[2:3], v[2:3], 0, s[6:7]
	s_mov_b32 m0, s44
	s_add_u32 s0, s24, 0xb0080
	global_load_lds_dwordx4 v[2:3], off
	v_lshl_add_u64 v[0:1], v[0:1], 0, s[6:7]
	s_mov_b32 m0, s45
	s_addc_u32 s1, s25, 0
	global_load_lds_dwordx4 v[0:1], off
	s_add_i32 m0, s39, 0x1c000
	v_lshl_add_u64 v[0:1], s[0:1], 0, v[158:159]
	global_load_lds_dwordx4 v[0:1], off
	v_lshl_add_u64 v[0:1], s[0:1], 0, v[162:163]
	s_add_i32 m0, s39, 0x1e000
	s_mov_b64 s[0:1], 0xb0080
	global_load_lds_dwordx4 v[0:1], off
	v_bfe_u32 v1, v8, 4, 2
	v_and_b32_e32 v0, 15, v8
	v_lshlrev_b32_e32 v2, 3, v1
	v_lshlrev_b32_e32 v1, 4, v1
	v_lshl_or_b32 v200, s8, 6, v0
	v_lshl_or_b32 v0, v0, 6, v1
	v_lshlrev_b32_e32 v1, 2, v8
	v_and_b32_e32 v1, 32, v1
	v_bitop3_b32 v3, v0, s3, v1 bitop3:0xde
	v_bitop3_b32 v201, v0, s5, v1 bitop3:0xde
	v_lshrrev_b32_e32 v1, 1, v9
	v_mul_lo_u32 v0, v11, s4
	s_mov_b32 s5, 0xb000
	v_lshl_or_b32 v202, s2, 5, v2
	v_mad_u64_u32 v[0:1], s[2:3], v1, s5, v[0:1]
	v_or_b32_e32 v0, v0, v10
	v_add_lshl_u32 v0, v0, v12, 1
	v_mov_b32_e32 v1, v159
	v_lshl_add_u64 v[164:165], v[0:1], 0, s[0:1]
	v_lshrrev_b32_e32 v1, 1, v13
	v_mul_lo_u32 v0, v14, s4
	s_ashr_i32 s46, s17, 31
	s_ashr_i32 s47, s16, 31
	v_mad_u64_u32 v[0:1], s[2:3], v1, s5, v[0:1]
	s_waitcnt vmcnt(6)
	s_cmp_lg_u64 s[26:27], 0
	v_or_b32_e32 v0, v0, v15
	s_cselect_b64 s[8:9], -1, 0
	v_add_lshl_u32 v0, v0, v16, 1
	v_mov_b32_e32 v1, v159
	s_add_i32 s48, 0, 0x10000
	s_add_i32 s49, 0, 0x14000
	v_lshl_add_u64 v[166:167], v[0:1], 0, s[0:1]
	v_mov_b64_e32 v[168:169], 0x100
	v_mov_b64_e32 v[170:171], 0xff
	v_add_u32_e32 v203, s48, v201
	v_add_u32_e32 v204, s49, v201
	v_add_u32_e32 v205, 0, v3
	s_mov_b64 s[10:11], 0x20000
	s_mov_b64 s[12:13], 0x24000
	s_mov_b64 s[14:15], 0x28000
	s_mov_b64 s[18:19], 0x2c000
	s_barrier
	s_branch .LBB0_1871
.LBB0_1870:
	s_and_b64 vcc, exec, s[0:1]
	s_mov_b32 s54, s50
	s_mov_b32 s55, s53
	s_mov_b64 s[24:25], s[4:5]
	s_mov_b64 s[22:23], s[20:21]
	s_cbranch_vccnz .LBB0_1947
	v_mov_b64_e32 v[24:25], 0
	v_mov_b64_e32 v[26:27], 0
	v_mov_b64_e32 v[28:29], 0
	v_mov_b64_e32 v[30:31], 0
	v_mov_b64_e32 v[36:37], 0
	v_mov_b64_e32 v[38:39], 0
	v_mov_b64_e32 v[40:41], 0
	v_mov_b64_e32 v[42:43], 0
	v_mov_b64_e32 v[44:45], 0
	v_mov_b64_e32 v[46:47], 0
	v_mov_b64_e32 v[48:49], 0
	v_mov_b64_e32 v[50:51], 0
	v_mov_b64_e32 v[52:53], 0
	v_mov_b64_e32 v[54:55], 0
	v_mov_b64_e32 v[56:57], 0
	v_mov_b64_e32 v[58:59], 0
	v_mov_b64_e32 v[60:61], 0
	v_mov_b64_e32 v[62:63], 0
	v_mov_b64_e32 v[64:65], 0
	v_mov_b64_e32 v[66:67], 0
	v_mov_b64_e32 v[68:69], 0
	v_mov_b64_e32 v[70:71], 0
	v_mov_b64_e32 v[72:73], 0
	v_mov_b64_e32 v[74:75], 0
	v_mov_b64_e32 v[76:77], 0
	v_mov_b64_e32 v[78:79], 0
	v_mov_b64_e32 v[80:81], 0
	v_mov_b64_e32 v[82:83], 0
	v_mov_b64_e32 v[84:85], 0
	v_mov_b64_e32 v[86:87], 0
	v_mov_b64_e32 v[88:89], 0
	v_mov_b64_e32 v[90:91], 0
	v_mov_b64_e32 v[92:93], 0
	v_mov_b64_e32 v[94:95], 0
	v_mov_b64_e32 v[96:97], 0
	v_mov_b64_e32 v[98:99], 0
	v_mov_b64_e32 v[100:101], 0
	v_mov_b64_e32 v[102:103], 0
	v_mov_b64_e32 v[104:105], 0
	v_mov_b64_e32 v[106:107], 0
	v_mov_b64_e32 v[108:109], 0
	v_mov_b64_e32 v[110:111], 0
	v_mov_b64_e32 v[112:113], 0
	v_mov_b64_e32 v[114:115], 0
	v_mov_b64_e32 v[116:117], 0
	v_mov_b64_e32 v[118:119], 0
	v_mov_b64_e32 v[120:121], 0
	v_mov_b64_e32 v[122:123], 0
	v_mov_b64_e32 v[124:125], 0
	v_mov_b64_e32 v[126:127], 0

.LBB0_1881:
	s_add_u32 s56, s24, 0x100
	v_mov_b32_e32 v0, 0
	s_addc_u32 s57, s25, 0
	s_mov_b32 s58, -2
	v_mov_b32_e32 v1, v0
	v_mov_b32_e32 v2, v0
	v_mov_b32_e32 v3, v0
	v_mov_b32_e32 v4, v0
	v_mov_b32_e32 v5, v0
	v_mov_b32_e32 v6, v0
	v_mov_b32_e32 v7, v0
	v_mov_b32_e32 v16, v0
	v_mov_b32_e32 v17, v0
	v_mov_b32_e32 v18, v0
	v_mov_b32_e32 v19, v0
	v_mov_b32_e32 v20, v0
	v_mov_b32_e32 v21, v0
	v_mov_b32_e32 v22, v0
	v_mov_b32_e32 v23, v0
	v_mov_b32_e32 v32, v0
	v_mov_b32_e32 v33, v0
	v_mov_b32_e32 v34, v0
	v_mov_b32_e32 v35, v0
	s_waitcnt vmcnt(0)
	v_mov_b64_e32 v[8:9], 0
	v_mov_b64_e32 v[10:11], 0
	v_mov_b64_e32 v[12:13], 0
	v_mov_b64_e32 v[14:15], 0
	s_nop 0
	s_nop 0
	s_nop 0
	s_nop 0
	s_nop 0
	s_nop 0
	s_nop 0
	s_nop 0
	s_nop 0
	s_nop 0
	s_nop 0
	s_nop 0
	s_nop 0
	s_nop 0
